# GEMM tile order tuned so that consecutive workgroups share one weight panel; hand-written GEMM loops and scan as before
# speedup vs baseline: 1.1028x; 1.0086x over previous
.LBB0_193:
.Lgin0_tile:
	s_bfe_u32 s100, s36, 0x30005
	s_and_b32 s101, s36, 31
	s_lshr_b32 s82, s36, 8
	s_lshr_b32 s64, s100, 2
	s_lshl_b32 s64, s64, 5
	s_add_u32 s64, s64, s101
	s_lshl_b32 s82, s82, 2
	s_and_b32 s100, s100, 3
	s_add_u32 s82, s82, s100
	s_lshl_b32 s64, s64, 8
	s_lshl_b32 s82, s82, 8
	s_lshl_b32 s100, s64, 12
	s_add_u32 s100, s100, 0x6224000
	s_add_u32 s48, s92, s100
	s_addc_u32 s49, s93, 0
	s_and_b32 s49, s49, 0xffff
	s_mov_b32 s50, 0x100000
	s_mov_b32 s51, 0x20000
	s_lshl_b32 s100, s82, 12
	s_add_u32 s100, s100, 0x0
	s_add_u32 s52, s92, s100
	s_addc_u32 s53, s93, 0
	s_and_b32 s53, s53, 0xffff
	s_sub_u32 s100, 0x1380, s82
	s_min_u32 s100, s100, 0x100
	s_lshl_b32 s54, s100, 12
	s_mov_b32 s55, 0x20000
	s_mov_b32 s46, 0x40000
	s_mov_b32 s47, 0x80000
	s_mov_b32 s58, 0xc0000
	v_lshrrev_b32_e32 v128, 3, v190
	v_and_b32_e32 v129, 7, v190
	v_lshlrev_b32_e32 v129, 4, v129
	v_lshl_add_u32 v160, v128, 12, v129
	v_mul_u32_u24_e32 v130, 0x90, v128
	v_add_u32_e32 v170, v130, v129
	v_add_u32_e32 v171, 0x12000, v170
	v_and_b32_e32 v131, 31, v190
	v_bfe_u32 v132, v190, 5, 1
	v_bfe_u32 v133, v190, 6, 2
	v_bfe_u32 v134, v190, 8, 1
	v_lshl_add_u32 v135, v134, 7, v131
	v_mul_u32_u24_e32 v135, 0x90, v135
	v_lshl_add_u32 v175, v132, 4, v135
	v_lshl_add_u32 v136, v133, 6, v131
	v_mul_u32_u24_e32 v136, 0x90, v136
	v_lshl_add_u32 v136, v132, 4, v136
	v_add_u32_e32 v254, 0x12000, v136
	v_mov_b32_e32 v0, 0
	v_mov_b32_e32 v1, 0
	v_mov_b32_e32 v2, 0
	v_mov_b32_e32 v3, 0
	v_mov_b32_e32 v4, 0
	v_mov_b32_e32 v5, 0
	v_mov_b32_e32 v6, 0
	v_mov_b32_e32 v7, 0
	v_mov_b32_e32 v8, 0
	v_mov_b32_e32 v9, 0
	v_mov_b32_e32 v10, 0
	v_mov_b32_e32 v11, 0
	v_mov_b32_e32 v12, 0
	v_mov_b32_e32 v13, 0
	v_mov_b32_e32 v14, 0
	v_mov_b32_e32 v15, 0
	v_mov_b32_e32 v16, 0
	v_mov_b32_e32 v17, 0
	v_mov_b32_e32 v18, 0
	v_mov_b32_e32 v19, 0
	v_mov_b32_e32 v20, 0
	v_mov_b32_e32 v21, 0
	v_mov_b32_e32 v22, 0
	v_mov_b32_e32 v23, 0
	v_mov_b32_e32 v24, 0
	v_mov_b32_e32 v25, 0
	v_mov_b32_e32 v26, 0
	v_mov_b32_e32 v27, 0
	v_mov_b32_e32 v28, 0
	v_mov_b32_e32 v29, 0
	v_mov_b32_e32 v30, 0
	v_mov_b32_e32 v31, 0
	v_mov_b32_e32 v32, 0
	v_mov_b32_e32 v33, 0
	v_mov_b32_e32 v34, 0
	v_mov_b32_e32 v35, 0
	v_mov_b32_e32 v36, 0
	v_mov_b32_e32 v37, 0
	v_mov_b32_e32 v38, 0
	v_mov_b32_e32 v39, 0
	v_mov_b32_e32 v40, 0
	v_mov_b32_e32 v41, 0
	v_mov_b32_e32 v42, 0
	v_mov_b32_e32 v43, 0
	v_mov_b32_e32 v44, 0
	v_mov_b32_e32 v45, 0
	v_mov_b32_e32 v46, 0
	v_mov_b32_e32 v47, 0
	v_mov_b32_e32 v48, 0
	v_mov_b32_e32 v49, 0
	v_mov_b32_e32 v50, 0
	v_mov_b32_e32 v51, 0
	v_mov_b32_e32 v52, 0
	v_mov_b32_e32 v53, 0
	v_mov_b32_e32 v54, 0
	v_mov_b32_e32 v55, 0
	v_mov_b32_e32 v56, 0
	v_mov_b32_e32 v57, 0
	v_mov_b32_e32 v58, 0
	v_mov_b32_e32 v59, 0
	v_mov_b32_e32 v60, 0
	v_mov_b32_e32 v61, 0
	v_mov_b32_e32 v62, 0
	v_mov_b32_e32 v63, 0
	v_mov_b32_e32 v64, 0
	v_mov_b32_e32 v65, 0
	v_mov_b32_e32 v66, 0
	v_mov_b32_e32 v67, 0
	v_mov_b32_e32 v68, 0
	v_mov_b32_e32 v69, 0
	v_mov_b32_e32 v70, 0
	v_mov_b32_e32 v71, 0
	v_mov_b32_e32 v72, 0
	v_mov_b32_e32 v73, 0
	v_mov_b32_e32 v74, 0
	v_mov_b32_e32 v75, 0
	v_mov_b32_e32 v76, 0
	v_mov_b32_e32 v77, 0
	v_mov_b32_e32 v78, 0
	v_mov_b32_e32 v79, 0
	v_mov_b32_e32 v80, 0
	v_mov_b32_e32 v81, 0
	v_mov_b32_e32 v82, 0
	v_mov_b32_e32 v83, 0
	v_mov_b32_e32 v84, 0
	v_mov_b32_e32 v85, 0
	v_mov_b32_e32 v86, 0
	v_mov_b32_e32 v87, 0
	v_mov_b32_e32 v88, 0
	v_mov_b32_e32 v89, 0
	v_mov_b32_e32 v90, 0
	v_mov_b32_e32 v91, 0
	v_mov_b32_e32 v92, 0
	v_mov_b32_e32 v93, 0
	v_mov_b32_e32 v94, 0
	v_mov_b32_e32 v95, 0
	v_mov_b32_e32 v96, 0
	v_mov_b32_e32 v97, 0
	v_mov_b32_e32 v98, 0
	v_mov_b32_e32 v99, 0
	v_mov_b32_e32 v100, 0
	v_mov_b32_e32 v101, 0
	v_mov_b32_e32 v102, 0
	v_mov_b32_e32 v103, 0
	v_mov_b32_e32 v104, 0
	v_mov_b32_e32 v105, 0
	v_mov_b32_e32 v106, 0
	v_mov_b32_e32 v107, 0
	v_mov_b32_e32 v108, 0
	v_mov_b32_e32 v109, 0
	v_mov_b32_e32 v110, 0
	v_mov_b32_e32 v111, 0
	v_mov_b32_e32 v112, 0
	v_mov_b32_e32 v113, 0
	v_mov_b32_e32 v114, 0
	v_mov_b32_e32 v115, 0
	v_mov_b32_e32 v116, 0
	v_mov_b32_e32 v117, 0
	v_mov_b32_e32 v118, 0
	v_mov_b32_e32 v119, 0
	v_mov_b32_e32 v120, 0
	v_mov_b32_e32 v121, 0
	v_mov_b32_e32 v122, 0
	v_mov_b32_e32 v123, 0
	v_mov_b32_e32 v124, 0
	v_mov_b32_e32 v125, 0
	v_mov_b32_e32 v126, 0
	v_mov_b32_e32 v127, 0
	v_mov_b32_e32 v192, 0
	v_mov_b32_e32 v193, 0
	v_mov_b32_e32 v194, 0
	v_mov_b32_e32 v195, 0
	v_mov_b32_e32 v196, 0
	v_mov_b32_e32 v197, 0
	v_mov_b32_e32 v198, 0
	v_mov_b32_e32 v199, 0
	v_mov_b32_e32 v200, 0
	v_mov_b32_e32 v201, 0
	v_mov_b32_e32 v202, 0
	v_mov_b32_e32 v203, 0
	v_mov_b32_e32 v204, 0
	v_mov_b32_e32 v205, 0
	v_mov_b32_e32 v206, 0
	v_mov_b32_e32 v207, 0
	v_mov_b32_e32 v208, 0
	v_mov_b32_e32 v209, 0
	v_mov_b32_e32 v210, 0
	v_mov_b32_e32 v211, 0
	v_mov_b32_e32 v212, 0
	v_mov_b32_e32 v213, 0
	v_mov_b32_e32 v214, 0
	v_mov_b32_e32 v215, 0
	v_mov_b32_e32 v188, 0
	v_mov_b32_e32 v189, 0
	buffer_load_dwordx4 v[216:219], v160, s[48:51], 0 offen
	buffer_load_dwordx4 v[220:223], v160, s[48:51], s46 offen
	buffer_load_dwordx4 v[224:227], v160, s[48:51], s47 offen
	buffer_load_dwordx4 v[228:231], v160, s[48:51], s58 offen
	buffer_load_dwordx4 v[232:235], v160, s[52:55], 0 offen
	buffer_load_dwordx4 v[236:239], v160, s[52:55], s46 offen
	buffer_load_dwordx4 v[152:155], v160, s[52:55], s47 offen
	buffer_load_dwordx4 v[156:159], v160, s[52:55], s58 offen
	v_add_u32_e32 v160, 0x80, v160
	buffer_load_dwordx4 v[162:165], v160, s[48:51], 0 offen
	buffer_load_dwordx4 v[166:169], v160, s[48:51], s46 offen
	buffer_load_dwordx4 v[176:179], v160, s[48:51], s47 offen
	buffer_load_dwordx4 v[180:183], v160, s[48:51], s58 offen
	buffer_load_dwordx4 v[184:187], v160, s[52:55], 0 offen
	buffer_load_dwordx4 v[242:245], v160, s[52:55], s46 offen
	buffer_load_dwordx4 v[246:249], v160, s[52:55], s47 offen
	buffer_load_dwordx4 v[250:253], v160, s[52:55], s58 offen
	v_add_u32_e32 v160, 0x80, v160
	s_waitcnt vmcnt(8)
	ds_write_b128 v170, v[216:219] offset:0
	ds_write_b128 v170, v[220:223] offset:9216
	ds_write_b128 v170, v[224:227] offset:18432
	ds_write_b128 v170, v[228:231] offset:27648
	ds_write_b128 v171, v[232:235] offset:0
	ds_write_b128 v171, v[236:239] offset:9216
	ds_write_b128 v171, v[152:155] offset:18432
	ds_write_b128 v171, v[156:159] offset:27648
	buffer_load_dwordx4 v[216:219], v160, s[48:51], 0 offen
	buffer_load_dwordx4 v[220:223], v160, s[48:51], s46 offen
	buffer_load_dwordx4 v[224:227], v160, s[48:51], s47 offen
	buffer_load_dwordx4 v[228:231], v160, s[48:51], s58 offen
	buffer_load_dwordx4 v[232:235], v160, s[52:55], 0 offen
	buffer_load_dwordx4 v[236:239], v160, s[52:55], s46 offen
	buffer_load_dwordx4 v[152:155], v160, s[52:55], s47 offen
	buffer_load_dwordx4 v[156:159], v160, s[52:55], s58 offen
	v_add_u32_e32 v160, 0x80, v160
	s_waitcnt lgkmcnt(0)
	s_barrier
	s_movk_i32 s59, 14

.LBB0_786:
.Lgout0_tile:
	s_bfe_u32 s20, s5, 0x30005
	s_and_b32 s21, s5, 31
	s_lshr_b32 s7, s5, 8
	s_lshl_b32 s6, s7, 5
	s_lshr_b32 s7, s20, 3
	s_lshl_b32 s7, s7, 5
	s_add_u32 s6, s6, s7
	s_lshr_b32 s7, s21, 0
	s_add_u32 s6, s6, s7
	s_and_b32 s7, s20, 7
	s_lshl_b32 s7, s7, 0
	s_and_b32 s21, s21, 0
	s_add_u32 s7, s7, s21
	s_lshl_b32 s6, s6, 8
	s_lshl_b32 s7, s7, 8
	s_lshl_b32 s20, s6, 12
	s_add_u32 s20, s20, 0xe224000
	s_add_u32 s8, s92, s20
	s_addc_u32 s9, s93, 0
	s_and_b32 s9, s9, 0xffff
	s_mov_b32 s10, 0x100000
	s_mov_b32 s11, 0x20000
	s_lshl_b32 s20, s7, 12
	s_add_u32 s20, s20, 0x1380000
	s_add_u32 s24, s92, s20
	s_addc_u32 s25, s93, 0
	s_and_b32 s25, s25, 0xffff
	s_sub_u32 s20, 0x800, s7
	s_min_u32 s20, s20, 0x100
	s_lshl_b32 s26, s20, 12
	s_mov_b32 s27, 0x20000
	s_mov_b32 s28, 0x40000
	s_mov_b32 s29, 0x80000
	s_mov_b32 s30, 0xc0000
	v_lshrrev_b32_e32 v128, 3, v190
	v_and_b32_e32 v129, 7, v190
	v_lshlrev_b32_e32 v129, 4, v129
	v_lshl_add_u32 v160, v128, 12, v129
	v_mul_u32_u24_e32 v130, 0x90, v128
	v_add_u32_e32 v170, v130, v129
	v_add_u32_e32 v171, 0x12000, v170
	v_and_b32_e32 v131, 31, v190
	v_bfe_u32 v132, v190, 5, 1
	v_bfe_u32 v133, v190, 6, 2
	v_bfe_u32 v134, v190, 8, 1
	v_lshl_add_u32 v135, v134, 7, v131
	v_mul_u32_u24_e32 v135, 0x90, v135
	v_lshl_add_u32 v175, v132, 4, v135
	v_lshl_add_u32 v136, v133, 6, v131
	v_mul_u32_u24_e32 v136, 0x90, v136
	v_lshl_add_u32 v136, v132, 4, v136
	v_add_u32_e32 v254, 0x12000, v136
	v_mov_b32_e32 v0, 0
	v_mov_b32_e32 v1, 0
	v_mov_b32_e32 v2, 0
	v_mov_b32_e32 v3, 0
	v_mov_b32_e32 v4, 0
	v_mov_b32_e32 v5, 0
	v_mov_b32_e32 v6, 0
	v_mov_b32_e32 v7, 0
	v_mov_b32_e32 v8, 0
	v_mov_b32_e32 v9, 0
	v_mov_b32_e32 v10, 0
	v_mov_b32_e32 v11, 0
	v_mov_b32_e32 v12, 0
	v_mov_b32_e32 v13, 0
	v_mov_b32_e32 v14, 0
	v_mov_b32_e32 v15, 0
	v_mov_b32_e32 v16, 0
	v_mov_b32_e32 v17, 0
	v_mov_b32_e32 v18, 0
	v_mov_b32_e32 v19, 0
	v_mov_b32_e32 v20, 0
	v_mov_b32_e32 v21, 0
	v_mov_b32_e32 v22, 0
	v_mov_b32_e32 v23, 0
	v_mov_b32_e32 v24, 0
	v_mov_b32_e32 v25, 0
	v_mov_b32_e32 v26, 0
	v_mov_b32_e32 v27, 0
	v_mov_b32_e32 v28, 0
	v_mov_b32_e32 v29, 0
	v_mov_b32_e32 v30, 0
	v_mov_b32_e32 v31, 0
	v_mov_b32_e32 v32, 0
	v_mov_b32_e32 v33, 0
	v_mov_b32_e32 v34, 0
	v_mov_b32_e32 v35, 0
	v_mov_b32_e32 v36, 0
	v_mov_b32_e32 v37, 0
	v_mov_b32_e32 v38, 0
	v_mov_b32_e32 v39, 0
	v_mov_b32_e32 v40, 0
	v_mov_b32_e32 v41, 0
	v_mov_b32_e32 v42, 0
	v_mov_b32_e32 v43, 0
	v_mov_b32_e32 v44, 0
	v_mov_b32_e32 v45, 0
	v_mov_b32_e32 v46, 0
	v_mov_b32_e32 v47, 0
	v_mov_b32_e32 v48, 0
	v_mov_b32_e32 v49, 0
	v_mov_b32_e32 v50, 0
	v_mov_b32_e32 v51, 0
	v_mov_b32_e32 v52, 0
	v_mov_b32_e32 v53, 0
	v_mov_b32_e32 v54, 0
	v_mov_b32_e32 v55, 0
	v_mov_b32_e32 v56, 0
	v_mov_b32_e32 v57, 0
	v_mov_b32_e32 v58, 0
	v_mov_b32_e32 v59, 0
	v_mov_b32_e32 v60, 0
	v_mov_b32_e32 v61, 0
	v_mov_b32_e32 v62, 0
	v_mov_b32_e32 v63, 0
	v_mov_b32_e32 v64, 0
	v_mov_b32_e32 v65, 0
	v_mov_b32_e32 v66, 0
	v_mov_b32_e32 v67, 0
	v_mov_b32_e32 v68, 0
	v_mov_b32_e32 v69, 0
	v_mov_b32_e32 v70, 0
	v_mov_b32_e32 v71, 0
	v_mov_b32_e32 v72, 0
	v_mov_b32_e32 v73, 0
	v_mov_b32_e32 v74, 0
	v_mov_b32_e32 v75, 0
	v_mov_b32_e32 v76, 0
	v_mov_b32_e32 v77, 0
	v_mov_b32_e32 v78, 0
	v_mov_b32_e32 v79, 0
	v_mov_b32_e32 v80, 0
	v_mov_b32_e32 v81, 0
	v_mov_b32_e32 v82, 0
	v_mov_b32_e32 v83, 0
	v_mov_b32_e32 v84, 0
	v_mov_b32_e32 v85, 0
	v_mov_b32_e32 v86, 0
	v_mov_b32_e32 v87, 0
	v_mov_b32_e32 v88, 0
	v_mov_b32_e32 v89, 0
	v_mov_b32_e32 v90, 0
	v_mov_b32_e32 v91, 0
	v_mov_b32_e32 v92, 0
	v_mov_b32_e32 v93, 0
	v_mov_b32_e32 v94, 0
	v_mov_b32_e32 v95, 0
	v_mov_b32_e32 v96, 0
	v_mov_b32_e32 v97, 0
	v_mov_b32_e32 v98, 0
	v_mov_b32_e32 v99, 0
	v_mov_b32_e32 v100, 0
	v_mov_b32_e32 v101, 0
	v_mov_b32_e32 v102, 0
	v_mov_b32_e32 v103, 0
	v_mov_b32_e32 v104, 0
	v_mov_b32_e32 v105, 0
	v_mov_b32_e32 v106, 0
	v_mov_b32_e32 v107, 0
	v_mov_b32_e32 v108, 0
	v_mov_b32_e32 v109, 0
	v_mov_b32_e32 v110, 0
	v_mov_b32_e32 v111, 0
	v_mov_b32_e32 v112, 0
	v_mov_b32_e32 v113, 0
	v_mov_b32_e32 v114, 0
	v_mov_b32_e32 v115, 0
	v_mov_b32_e32 v116, 0
	v_mov_b32_e32 v117, 0
	v_mov_b32_e32 v118, 0
	v_mov_b32_e32 v119, 0
	v_mov_b32_e32 v120, 0
	v_mov_b32_e32 v121, 0
	v_mov_b32_e32 v122, 0
	v_mov_b32_e32 v123, 0
	v_mov_b32_e32 v124, 0
	v_mov_b32_e32 v125, 0
	v_mov_b32_e32 v126, 0
	v_mov_b32_e32 v127, 0
	v_mov_b32_e32 v192, 0
	v_mov_b32_e32 v193, 0
	v_mov_b32_e32 v194, 0
	v_mov_b32_e32 v195, 0
	v_mov_b32_e32 v196, 0
	v_mov_b32_e32 v197, 0
	v_mov_b32_e32 v198, 0
	v_mov_b32_e32 v199, 0
	v_mov_b32_e32 v200, 0
	v_mov_b32_e32 v201, 0
	v_mov_b32_e32 v202, 0
	v_mov_b32_e32 v203, 0
	v_mov_b32_e32 v204, 0
	v_mov_b32_e32 v205, 0
	v_mov_b32_e32 v206, 0
	v_mov_b32_e32 v207, 0
	v_mov_b32_e32 v208, 0
	v_mov_b32_e32 v209, 0
	v_mov_b32_e32 v210, 0
	v_mov_b32_e32 v211, 0
	v_mov_b32_e32 v212, 0
	v_mov_b32_e32 v213, 0
	v_mov_b32_e32 v214, 0
	v_mov_b32_e32 v215, 0
	v_mov_b32_e32 v188, 0
	v_mov_b32_e32 v189, 0
	buffer_load_dwordx4 v[216:219], v160, s[8:11], 0 offen
	buffer_load_dwordx4 v[220:223], v160, s[8:11], s28 offen
	buffer_load_dwordx4 v[224:227], v160, s[8:11], s29 offen
	buffer_load_dwordx4 v[228:231], v160, s[8:11], s30 offen
	buffer_load_dwordx4 v[232:235], v160, s[24:27], 0 offen
	buffer_load_dwordx4 v[236:239], v160, s[24:27], s28 offen
	buffer_load_dwordx4 v[152:155], v160, s[24:27], s29 offen
	buffer_load_dwordx4 v[156:159], v160, s[24:27], s30 offen
	v_add_u32_e32 v160, 0x80, v160
	buffer_load_dwordx4 v[162:165], v160, s[8:11], 0 offen
	buffer_load_dwordx4 v[166:169], v160, s[8:11], s28 offen
	buffer_load_dwordx4 v[176:179], v160, s[8:11], s29 offen
	buffer_load_dwordx4 v[180:183], v160, s[8:11], s30 offen
	buffer_load_dwordx4 v[184:187], v160, s[24:27], 0 offen
	buffer_load_dwordx4 v[242:245], v160, s[24:27], s28 offen
	buffer_load_dwordx4 v[246:249], v160, s[24:27], s29 offen
	buffer_load_dwordx4 v[250:253], v160, s[24:27], s30 offen
	v_add_u32_e32 v160, 0x80, v160
	s_waitcnt vmcnt(8)
	ds_write_b128 v170, v[216:219] offset:0
	ds_write_b128 v170, v[220:223] offset:9216
	ds_write_b128 v170, v[224:227] offset:18432
	ds_write_b128 v170, v[228:231] offset:27648
	ds_write_b128 v171, v[232:235] offset:0
	ds_write_b128 v171, v[236:239] offset:9216
	ds_write_b128 v171, v[152:155] offset:18432
	ds_write_b128 v171, v[156:159] offset:27648
	buffer_load_dwordx4 v[216:219], v160, s[8:11], 0 offen
	buffer_load_dwordx4 v[220:223], v160, s[8:11], s28 offen
	buffer_load_dwordx4 v[224:227], v160, s[8:11], s29 offen
	buffer_load_dwordx4 v[228:231], v160, s[8:11], s30 offen
	buffer_load_dwordx4 v[232:235], v160, s[24:27], 0 offen
	buffer_load_dwordx4 v[236:239], v160, s[24:27], s28 offen
	buffer_load_dwordx4 v[152:155], v160, s[24:27], s29 offen
	buffer_load_dwordx4 v[156:159], v160, s[24:27], s30 offen
	v_add_u32_e32 v160, 0x80, v160
	s_waitcnt lgkmcnt(0)
	s_barrier
	s_movk_i32 s31, 14

.LBB0_1415:
.Lgwq0_tile:
	s_bfe_u32 s100, s39, 0x30005
	s_and_b32 s101, s39, 31
	s_lshr_b32 s82, s39, 8
	s_lshl_b32 s64, s82, 5
	s_lshr_b32 s82, s100, 3
	s_lshl_b32 s82, s82, 5
	s_add_u32 s64, s64, s82
	s_lshr_b32 s82, s101, 0
	s_add_u32 s64, s64, s82
	s_and_b32 s82, s100, 7
	s_lshl_b32 s82, s82, 0
	s_and_b32 s101, s101, 0
	s_add_u32 s82, s82, s101
	s_lshl_b32 s64, s64, 8
	s_lshl_b32 s82, s82, 8
	s_lshl_b32 s100, s64, 12
	s_add_u32 s100, s100, 0x6224000
	s_add_u32 s48, s92, s100
	s_addc_u32 s49, s93, 0
	s_and_b32 s49, s49, 0xffff
	s_mov_b32 s50, 0x100000
	s_mov_b32 s51, 0x20000
	s_lshl_b32 s100, s82, 12
	s_add_u32 s100, s100, 0x3b80000
	s_add_u32 s52, s92, s100
	s_addc_u32 s53, s93, 0
	s_and_b32 s53, s53, 0xffff
	s_sub_u32 s100, 0x800, s82
	s_min_u32 s100, s100, 0x100
	s_lshl_b32 s54, s100, 12
	s_mov_b32 s55, 0x20000
	s_mov_b32 s46, 0x40000
	s_mov_b32 s47, 0x80000
	s_mov_b32 s58, 0xc0000
	v_lshrrev_b32_e32 v128, 3, v190
	v_and_b32_e32 v129, 7, v190
	v_lshlrev_b32_e32 v129, 4, v129
	v_lshl_add_u32 v160, v128, 12, v129
	v_mul_u32_u24_e32 v130, 0x90, v128
	v_add_u32_e32 v170, v130, v129
	v_add_u32_e32 v171, 0x12000, v170
	v_and_b32_e32 v131, 31, v190
	v_bfe_u32 v132, v190, 5, 1
	v_bfe_u32 v133, v190, 6, 2
	v_bfe_u32 v134, v190, 8, 1
	v_lshl_add_u32 v135, v134, 7, v131
	v_mul_u32_u24_e32 v135, 0x90, v135
	v_lshl_add_u32 v175, v132, 4, v135
	v_lshl_add_u32 v136, v133, 6, v131
	v_mul_u32_u24_e32 v136, 0x90, v136
	v_lshl_add_u32 v136, v132, 4, v136
	v_add_u32_e32 v254, 0x12000, v136
	v_mov_b32_e32 v0, 0
	v_mov_b32_e32 v1, 0
	v_mov_b32_e32 v2, 0
	v_mov_b32_e32 v3, 0
	v_mov_b32_e32 v4, 0
	v_mov_b32_e32 v5, 0
	v_mov_b32_e32 v6, 0
	v_mov_b32_e32 v7, 0
	v_mov_b32_e32 v8, 0
	v_mov_b32_e32 v9, 0
	v_mov_b32_e32 v10, 0
	v_mov_b32_e32 v11, 0
	v_mov_b32_e32 v12, 0
	v_mov_b32_e32 v13, 0
	v_mov_b32_e32 v14, 0
	v_mov_b32_e32 v15, 0
	v_mov_b32_e32 v16, 0
	v_mov_b32_e32 v17, 0
	v_mov_b32_e32 v18, 0
	v_mov_b32_e32 v19, 0
	v_mov_b32_e32 v20, 0
	v_mov_b32_e32 v21, 0
	v_mov_b32_e32 v22, 0
	v_mov_b32_e32 v23, 0
	v_mov_b32_e32 v24, 0
	v_mov_b32_e32 v25, 0
	v_mov_b32_e32 v26, 0
	v_mov_b32_e32 v27, 0
	v_mov_b32_e32 v28, 0
	v_mov_b32_e32 v29, 0
	v_mov_b32_e32 v30, 0
	v_mov_b32_e32 v31, 0
	v_mov_b32_e32 v32, 0
	v_mov_b32_e32 v33, 0
	v_mov_b32_e32 v34, 0
	v_mov_b32_e32 v35, 0
	v_mov_b32_e32 v36, 0
	v_mov_b32_e32 v37, 0
	v_mov_b32_e32 v38, 0
	v_mov_b32_e32 v39, 0
	v_mov_b32_e32 v40, 0
	v_mov_b32_e32 v41, 0
	v_mov_b32_e32 v42, 0
	v_mov_b32_e32 v43, 0
	v_mov_b32_e32 v44, 0
	v_mov_b32_e32 v45, 0
	v_mov_b32_e32 v46, 0
	v_mov_b32_e32 v47, 0
	v_mov_b32_e32 v48, 0
	v_mov_b32_e32 v49, 0
	v_mov_b32_e32 v50, 0
	v_mov_b32_e32 v51, 0
	v_mov_b32_e32 v52, 0
	v_mov_b32_e32 v53, 0
	v_mov_b32_e32 v54, 0
	v_mov_b32_e32 v55, 0
	v_mov_b32_e32 v56, 0
	v_mov_b32_e32 v57, 0
	v_mov_b32_e32 v58, 0
	v_mov_b32_e32 v59, 0
	v_mov_b32_e32 v60, 0
	v_mov_b32_e32 v61, 0
	v_mov_b32_e32 v62, 0
	v_mov_b32_e32 v63, 0
	v_mov_b32_e32 v64, 0
	v_mov_b32_e32 v65, 0
	v_mov_b32_e32 v66, 0
	v_mov_b32_e32 v67, 0
	v_mov_b32_e32 v68, 0
	v_mov_b32_e32 v69, 0
	v_mov_b32_e32 v70, 0
	v_mov_b32_e32 v71, 0
	v_mov_b32_e32 v72, 0
	v_mov_b32_e32 v73, 0
	v_mov_b32_e32 v74, 0
	v_mov_b32_e32 v75, 0
	v_mov_b32_e32 v76, 0
	v_mov_b32_e32 v77, 0
	v_mov_b32_e32 v78, 0
	v_mov_b32_e32 v79, 0
	v_mov_b32_e32 v80, 0
	v_mov_b32_e32 v81, 0
	v_mov_b32_e32 v82, 0
	v_mov_b32_e32 v83, 0
	v_mov_b32_e32 v84, 0
	v_mov_b32_e32 v85, 0
	v_mov_b32_e32 v86, 0
	v_mov_b32_e32 v87, 0
	v_mov_b32_e32 v88, 0
	v_mov_b32_e32 v89, 0
	v_mov_b32_e32 v90, 0
	v_mov_b32_e32 v91, 0
	v_mov_b32_e32 v92, 0
	v_mov_b32_e32 v93, 0
	v_mov_b32_e32 v94, 0
	v_mov_b32_e32 v95, 0
	v_mov_b32_e32 v96, 0
	v_mov_b32_e32 v97, 0
	v_mov_b32_e32 v98, 0
	v_mov_b32_e32 v99, 0
	v_mov_b32_e32 v100, 0
	v_mov_b32_e32 v101, 0
	v_mov_b32_e32 v102, 0
	v_mov_b32_e32 v103, 0
	v_mov_b32_e32 v104, 0
	v_mov_b32_e32 v105, 0
	v_mov_b32_e32 v106, 0
	v_mov_b32_e32 v107, 0
	v_mov_b32_e32 v108, 0
	v_mov_b32_e32 v109, 0
	v_mov_b32_e32 v110, 0
	v_mov_b32_e32 v111, 0
	v_mov_b32_e32 v112, 0
	v_mov_b32_e32 v113, 0
	v_mov_b32_e32 v114, 0
	v_mov_b32_e32 v115, 0
	v_mov_b32_e32 v116, 0
	v_mov_b32_e32 v117, 0
	v_mov_b32_e32 v118, 0
	v_mov_b32_e32 v119, 0
	v_mov_b32_e32 v120, 0
	v_mov_b32_e32 v121, 0
	v_mov_b32_e32 v122, 0
	v_mov_b32_e32 v123, 0
	v_mov_b32_e32 v124, 0
	v_mov_b32_e32 v125, 0
	v_mov_b32_e32 v126, 0
	v_mov_b32_e32 v127, 0
	v_mov_b32_e32 v192, 0
	v_mov_b32_e32 v193, 0
	v_mov_b32_e32 v194, 0
	v_mov_b32_e32 v195, 0
	v_mov_b32_e32 v196, 0
	v_mov_b32_e32 v197, 0
	v_mov_b32_e32 v198, 0
	v_mov_b32_e32 v199, 0
	v_mov_b32_e32 v200, 0
	v_mov_b32_e32 v201, 0
	v_mov_b32_e32 v202, 0
	v_mov_b32_e32 v203, 0
	v_mov_b32_e32 v204, 0
	v_mov_b32_e32 v205, 0
	v_mov_b32_e32 v206, 0
	v_mov_b32_e32 v207, 0
	v_mov_b32_e32 v208, 0
	v_mov_b32_e32 v209, 0
	v_mov_b32_e32 v210, 0
	v_mov_b32_e32 v211, 0
	v_mov_b32_e32 v212, 0
	v_mov_b32_e32 v213, 0
	v_mov_b32_e32 v214, 0
	v_mov_b32_e32 v215, 0
	v_mov_b32_e32 v188, 0
	v_mov_b32_e32 v189, 0
	buffer_load_dwordx4 v[216:219], v160, s[48:51], 0 offen
	buffer_load_dwordx4 v[220:223], v160, s[48:51], s46 offen
	buffer_load_dwordx4 v[224:227], v160, s[48:51], s47 offen
	buffer_load_dwordx4 v[228:231], v160, s[48:51], s58 offen
	buffer_load_dwordx4 v[232:235], v160, s[52:55], 0 offen
	buffer_load_dwordx4 v[236:239], v160, s[52:55], s46 offen
	buffer_load_dwordx4 v[152:155], v160, s[52:55], s47 offen
	buffer_load_dwordx4 v[156:159], v160, s[52:55], s58 offen
	v_add_u32_e32 v160, 0x80, v160
	buffer_load_dwordx4 v[162:165], v160, s[48:51], 0 offen
	buffer_load_dwordx4 v[166:169], v160, s[48:51], s46 offen
	buffer_load_dwordx4 v[176:179], v160, s[48:51], s47 offen
	buffer_load_dwordx4 v[180:183], v160, s[48:51], s58 offen
	buffer_load_dwordx4 v[184:187], v160, s[52:55], 0 offen
	buffer_load_dwordx4 v[242:245], v160, s[52:55], s46 offen
	buffer_load_dwordx4 v[246:249], v160, s[52:55], s47 offen
	buffer_load_dwordx4 v[250:253], v160, s[52:55], s58 offen
	v_add_u32_e32 v160, 0x80, v160
	s_waitcnt vmcnt(8)
	ds_write_b128 v170, v[216:219] offset:0
	ds_write_b128 v170, v[220:223] offset:9216
	ds_write_b128 v170, v[224:227] offset:18432
	ds_write_b128 v170, v[228:231] offset:27648
	ds_write_b128 v171, v[232:235] offset:0
	ds_write_b128 v171, v[236:239] offset:9216
	ds_write_b128 v171, v[152:155] offset:18432
	ds_write_b128 v171, v[156:159] offset:27648
	buffer_load_dwordx4 v[216:219], v160, s[48:51], 0 offen
	buffer_load_dwordx4 v[220:223], v160, s[48:51], s46 offen
	buffer_load_dwordx4 v[224:227], v160, s[48:51], s47 offen
	buffer_load_dwordx4 v[228:231], v160, s[48:51], s58 offen
	buffer_load_dwordx4 v[232:235], v160, s[52:55], 0 offen
	buffer_load_dwordx4 v[236:239], v160, s[52:55], s46 offen
	buffer_load_dwordx4 v[152:155], v160, s[52:55], s47 offen
	buffer_load_dwordx4 v[156:159], v160, s[52:55], s58 offen
	v_add_u32_e32 v160, 0x80, v160
	s_waitcnt lgkmcnt(0)
	s_barrier
	s_movk_i32 s59, 14

.LBB0_2004:
.Lgout1_tile:
	s_bfe_u32 s20, s79, 0x30005
	s_and_b32 s21, s79, 31
	s_lshr_b32 s7, s79, 8
	s_lshl_b32 s6, s7, 5
	s_lshr_b32 s7, s20, 3
	s_lshl_b32 s7, s7, 5
	s_add_u32 s6, s6, s7
	s_lshr_b32 s7, s21, 0
	s_add_u32 s6, s6, s7
	s_and_b32 s7, s20, 7
	s_lshl_b32 s7, s7, 0
	s_and_b32 s21, s21, 0
	s_add_u32 s7, s7, s21
	s_lshl_b32 s6, s6, 8
	s_lshl_b32 s7, s7, 8
	s_lshl_b32 s20, s6, 12
	s_add_u32 s20, s20, 0x6224000
	s_add_u32 s8, s92, s20
	s_addc_u32 s9, s93, 0
	s_and_b32 s9, s9, 0xffff
	s_mov_b32 s10, 0x100000
	s_mov_b32 s11, 0x20000
	s_lshl_b32 s20, s7, 12
	s_add_u32 s20, s20, 0x3380000
	s_add_u32 s24, s92, s20
	s_addc_u32 s25, s93, 0
	s_and_b32 s25, s25, 0xffff
	s_sub_u32 s20, 0x800, s7
	s_min_u32 s20, s20, 0x100
	s_lshl_b32 s26, s20, 12
	s_mov_b32 s27, 0x20000
	s_mov_b32 s28, 0x40000
	s_mov_b32 s29, 0x80000
	s_mov_b32 s30, 0xc0000
	v_lshrrev_b32_e32 v128, 3, v190
	v_and_b32_e32 v129, 7, v190
	v_lshlrev_b32_e32 v129, 4, v129
	v_lshl_add_u32 v160, v128, 12, v129
	v_mul_u32_u24_e32 v130, 0x90, v128
	v_add_u32_e32 v170, v130, v129
	v_add_u32_e32 v171, 0x12000, v170
	v_and_b32_e32 v131, 31, v190
	v_bfe_u32 v132, v190, 5, 1
	v_bfe_u32 v133, v190, 6, 2
	v_bfe_u32 v134, v190, 8, 1
	v_lshl_add_u32 v135, v134, 7, v131
	v_mul_u32_u24_e32 v135, 0x90, v135
	v_lshl_add_u32 v175, v132, 4, v135
	v_lshl_add_u32 v136, v133, 6, v131
	v_mul_u32_u24_e32 v136, 0x90, v136
	v_lshl_add_u32 v136, v132, 4, v136
	v_add_u32_e32 v254, 0x12000, v136
	v_mov_b32_e32 v0, 0
	v_mov_b32_e32 v1, 0
	v_mov_b32_e32 v2, 0
	v_mov_b32_e32 v3, 0
	v_mov_b32_e32 v4, 0
	v_mov_b32_e32 v5, 0
	v_mov_b32_e32 v6, 0
	v_mov_b32_e32 v7, 0
	v_mov_b32_e32 v8, 0
	v_mov_b32_e32 v9, 0
	v_mov_b32_e32 v10, 0
	v_mov_b32_e32 v11, 0
	v_mov_b32_e32 v12, 0
	v_mov_b32_e32 v13, 0
	v_mov_b32_e32 v14, 0
	v_mov_b32_e32 v15, 0
	v_mov_b32_e32 v16, 0
	v_mov_b32_e32 v17, 0
	v_mov_b32_e32 v18, 0
	v_mov_b32_e32 v19, 0
	v_mov_b32_e32 v20, 0
	v_mov_b32_e32 v21, 0
	v_mov_b32_e32 v22, 0
	v_mov_b32_e32 v23, 0
	v_mov_b32_e32 v24, 0
	v_mov_b32_e32 v25, 0
	v_mov_b32_e32 v26, 0
	v_mov_b32_e32 v27, 0
	v_mov_b32_e32 v28, 0
	v_mov_b32_e32 v29, 0
	v_mov_b32_e32 v30, 0
	v_mov_b32_e32 v31, 0
	v_mov_b32_e32 v32, 0
	v_mov_b32_e32 v33, 0
	v_mov_b32_e32 v34, 0
	v_mov_b32_e32 v35, 0
	v_mov_b32_e32 v36, 0
	v_mov_b32_e32 v37, 0
	v_mov_b32_e32 v38, 0
	v_mov_b32_e32 v39, 0
	v_mov_b32_e32 v40, 0
	v_mov_b32_e32 v41, 0
	v_mov_b32_e32 v42, 0
	v_mov_b32_e32 v43, 0
	v_mov_b32_e32 v44, 0
	v_mov_b32_e32 v45, 0
	v_mov_b32_e32 v46, 0
	v_mov_b32_e32 v47, 0
	v_mov_b32_e32 v48, 0
	v_mov_b32_e32 v49, 0
	v_mov_b32_e32 v50, 0
	v_mov_b32_e32 v51, 0
	v_mov_b32_e32 v52, 0
	v_mov_b32_e32 v53, 0
	v_mov_b32_e32 v54, 0
	v_mov_b32_e32 v55, 0
	v_mov_b32_e32 v56, 0
	v_mov_b32_e32 v57, 0
	v_mov_b32_e32 v58, 0
	v_mov_b32_e32 v59, 0
	v_mov_b32_e32 v60, 0
	v_mov_b32_e32 v61, 0
	v_mov_b32_e32 v62, 0
	v_mov_b32_e32 v63, 0
	v_mov_b32_e32 v64, 0
	v_mov_b32_e32 v65, 0
	v_mov_b32_e32 v66, 0
	v_mov_b32_e32 v67, 0
	v_mov_b32_e32 v68, 0
	v_mov_b32_e32 v69, 0
	v_mov_b32_e32 v70, 0
	v_mov_b32_e32 v71, 0
	v_mov_b32_e32 v72, 0
	v_mov_b32_e32 v73, 0
	v_mov_b32_e32 v74, 0
	v_mov_b32_e32 v75, 0
	v_mov_b32_e32 v76, 0
	v_mov_b32_e32 v77, 0
	v_mov_b32_e32 v78, 0
	v_mov_b32_e32 v79, 0
	v_mov_b32_e32 v80, 0
	v_mov_b32_e32 v81, 0
	v_mov_b32_e32 v82, 0
	v_mov_b32_e32 v83, 0
	v_mov_b32_e32 v84, 0
	v_mov_b32_e32 v85, 0
	v_mov_b32_e32 v86, 0
	v_mov_b32_e32 v87, 0
	v_mov_b32_e32 v88, 0
	v_mov_b32_e32 v89, 0
	v_mov_b32_e32 v90, 0
	v_mov_b32_e32 v91, 0
	v_mov_b32_e32 v92, 0
	v_mov_b32_e32 v93, 0
	v_mov_b32_e32 v94, 0
	v_mov_b32_e32 v95, 0
	v_mov_b32_e32 v96, 0
	v_mov_b32_e32 v97, 0
	v_mov_b32_e32 v98, 0
	v_mov_b32_e32 v99, 0
	v_mov_b32_e32 v100, 0
	v_mov_b32_e32 v101, 0
	v_mov_b32_e32 v102, 0
	v_mov_b32_e32 v103, 0
	v_mov_b32_e32 v104, 0
	v_mov_b32_e32 v105, 0
	v_mov_b32_e32 v106, 0
	v_mov_b32_e32 v107, 0
	v_mov_b32_e32 v108, 0
	v_mov_b32_e32 v109, 0
	v_mov_b32_e32 v110, 0
	v_mov_b32_e32 v111, 0
	v_mov_b32_e32 v112, 0
	v_mov_b32_e32 v113, 0
	v_mov_b32_e32 v114, 0
	v_mov_b32_e32 v115, 0
	v_mov_b32_e32 v116, 0
	v_mov_b32_e32 v117, 0
	v_mov_b32_e32 v118, 0
	v_mov_b32_e32 v119, 0
	v_mov_b32_e32 v120, 0
	v_mov_b32_e32 v121, 0
	v_mov_b32_e32 v122, 0
	v_mov_b32_e32 v123, 0
	v_mov_b32_e32 v124, 0
	v_mov_b32_e32 v125, 0
	v_mov_b32_e32 v126, 0
	v_mov_b32_e32 v127, 0
	v_mov_b32_e32 v192, 0
	v_mov_b32_e32 v193, 0
	v_mov_b32_e32 v194, 0
	v_mov_b32_e32 v195, 0
	v_mov_b32_e32 v196, 0
	v_mov_b32_e32 v197, 0
	v_mov_b32_e32 v198, 0
	v_mov_b32_e32 v199, 0
	v_mov_b32_e32 v200, 0
	v_mov_b32_e32 v201, 0
	v_mov_b32_e32 v202, 0
	v_mov_b32_e32 v203, 0
	v_mov_b32_e32 v204, 0
	v_mov_b32_e32 v205, 0
	v_mov_b32_e32 v206, 0
	v_mov_b32_e32 v207, 0
	v_mov_b32_e32 v208, 0
	v_mov_b32_e32 v209, 0
	v_mov_b32_e32 v210, 0
	v_mov_b32_e32 v211, 0
	v_mov_b32_e32 v212, 0
	v_mov_b32_e32 v213, 0
	v_mov_b32_e32 v214, 0
	v_mov_b32_e32 v215, 0
	v_mov_b32_e32 v188, 0
	v_mov_b32_e32 v189, 0
	buffer_load_dwordx4 v[216:219], v160, s[8:11], 0 offen
	buffer_load_dwordx4 v[220:223], v160, s[8:11], s28 offen
	buffer_load_dwordx4 v[224:227], v160, s[8:11], s29 offen
	buffer_load_dwordx4 v[228:231], v160, s[8:11], s30 offen
	buffer_load_dwordx4 v[232:235], v160, s[24:27], 0 offen
	buffer_load_dwordx4 v[236:239], v160, s[24:27], s28 offen
	buffer_load_dwordx4 v[152:155], v160, s[24:27], s29 offen
	buffer_load_dwordx4 v[156:159], v160, s[24:27], s30 offen
	v_add_u32_e32 v160, 0x80, v160
	buffer_load_dwordx4 v[162:165], v160, s[8:11], 0 offen
	buffer_load_dwordx4 v[166:169], v160, s[8:11], s28 offen
	buffer_load_dwordx4 v[176:179], v160, s[8:11], s29 offen
	buffer_load_dwordx4 v[180:183], v160, s[8:11], s30 offen
	buffer_load_dwordx4 v[184:187], v160, s[24:27], 0 offen
	buffer_load_dwordx4 v[242:245], v160, s[24:27], s28 offen
	buffer_load_dwordx4 v[246:249], v160, s[24:27], s29 offen
	buffer_load_dwordx4 v[250:253], v160, s[24:27], s30 offen
	v_add_u32_e32 v160, 0x80, v160
	s_waitcnt vmcnt(8)
	ds_write_b128 v170, v[216:219] offset:0
	ds_write_b128 v170, v[220:223] offset:9216
	ds_write_b128 v170, v[224:227] offset:18432
	ds_write_b128 v170, v[228:231] offset:27648
	ds_write_b128 v171, v[232:235] offset:0
	ds_write_b128 v171, v[236:239] offset:9216
	ds_write_b128 v171, v[152:155] offset:18432
	ds_write_b128 v171, v[156:159] offset:27648
	buffer_load_dwordx4 v[216:219], v160, s[8:11], 0 offen
	buffer_load_dwordx4 v[220:223], v160, s[8:11], s28 offen
	buffer_load_dwordx4 v[224:227], v160, s[8:11], s29 offen
	buffer_load_dwordx4 v[228:231], v160, s[8:11], s30 offen
	buffer_load_dwordx4 v[232:235], v160, s[24:27], 0 offen
	buffer_load_dwordx4 v[236:239], v160, s[24:27], s28 offen
	buffer_load_dwordx4 v[152:155], v160, s[24:27], s29 offen
	buffer_load_dwordx4 v[156:159], v160, s[24:27], s30 offen
	v_add_u32_e32 v160, 0x80, v160
	s_waitcnt lgkmcnt(0)
	s_barrier
	s_movk_i32 s31, 14

.LBB0_2633:
.Lgwq1_tile:
	s_bfe_u32 s100, s38, 0x30005
	s_and_b32 s101, s38, 31
	s_lshr_b32 s82, s38, 8
	s_lshl_b32 s64, s82, 5
	s_lshr_b32 s82, s100, 3
	s_lshl_b32 s82, s82, 5
	s_add_u32 s64, s64, s82
	s_lshr_b32 s82, s101, 0
	s_add_u32 s64, s64, s82
	s_and_b32 s82, s100, 7
	s_lshl_b32 s82, s82, 0
	s_and_b32 s101, s101, 0
	s_add_u32 s82, s82, s101
	s_lshl_b32 s64, s64, 8
	s_lshl_b32 s82, s82, 8
	s_lshl_b32 s100, s64, 12
	s_add_u32 s100, s100, 0x6224000
	s_add_u32 s48, s92, s100
	s_addc_u32 s49, s93, 0
	s_and_b32 s49, s49, 0xffff
	s_mov_b32 s50, 0x100000
	s_mov_b32 s51, 0x20000
	s_lshl_b32 s100, s82, 12
	s_add_u32 s100, s100, 0x4380000
	s_add_u32 s52, s92, s100
	s_addc_u32 s53, s93, 0
	s_and_b32 s53, s53, 0xffff
	s_sub_u32 s100, 0x800, s82
	s_min_u32 s100, s100, 0x100
	s_lshl_b32 s54, s100, 12
	s_mov_b32 s55, 0x20000
	s_mov_b32 s46, 0x40000
	s_mov_b32 s47, 0x80000
	s_mov_b32 s58, 0xc0000
	v_lshrrev_b32_e32 v128, 3, v190
	v_and_b32_e32 v129, 7, v190
	v_lshlrev_b32_e32 v129, 4, v129
	v_lshl_add_u32 v160, v128, 12, v129
	v_mul_u32_u24_e32 v130, 0x90, v128
	v_add_u32_e32 v170, v130, v129
	v_add_u32_e32 v171, 0x12000, v170
	v_and_b32_e32 v131, 31, v190
	v_bfe_u32 v132, v190, 5, 1
	v_bfe_u32 v133, v190, 6, 2
	v_bfe_u32 v134, v190, 8, 1
	v_lshl_add_u32 v135, v134, 7, v131
	v_mul_u32_u24_e32 v135, 0x90, v135
	v_lshl_add_u32 v175, v132, 4, v135
	v_lshl_add_u32 v136, v133, 6, v131
	v_mul_u32_u24_e32 v136, 0x90, v136
	v_lshl_add_u32 v136, v132, 4, v136
	v_add_u32_e32 v254, 0x12000, v136
	v_mov_b32_e32 v0, 0
	v_mov_b32_e32 v1, 0
	v_mov_b32_e32 v2, 0
	v_mov_b32_e32 v3, 0
	v_mov_b32_e32 v4, 0
	v_mov_b32_e32 v5, 0
	v_mov_b32_e32 v6, 0
	v_mov_b32_e32 v7, 0
	v_mov_b32_e32 v8, 0
	v_mov_b32_e32 v9, 0
	v_mov_b32_e32 v10, 0
	v_mov_b32_e32 v11, 0
	v_mov_b32_e32 v12, 0
	v_mov_b32_e32 v13, 0
	v_mov_b32_e32 v14, 0
	v_mov_b32_e32 v15, 0
	v_mov_b32_e32 v16, 0
	v_mov_b32_e32 v17, 0
	v_mov_b32_e32 v18, 0
	v_mov_b32_e32 v19, 0
	v_mov_b32_e32 v20, 0
	v_mov_b32_e32 v21, 0
	v_mov_b32_e32 v22, 0
	v_mov_b32_e32 v23, 0
	v_mov_b32_e32 v24, 0
	v_mov_b32_e32 v25, 0
	v_mov_b32_e32 v26, 0
	v_mov_b32_e32 v27, 0
	v_mov_b32_e32 v28, 0
	v_mov_b32_e32 v29, 0
	v_mov_b32_e32 v30, 0
	v_mov_b32_e32 v31, 0
	v_mov_b32_e32 v32, 0
	v_mov_b32_e32 v33, 0
	v_mov_b32_e32 v34, 0
	v_mov_b32_e32 v35, 0
	v_mov_b32_e32 v36, 0
	v_mov_b32_e32 v37, 0
	v_mov_b32_e32 v38, 0
	v_mov_b32_e32 v39, 0
	v_mov_b32_e32 v40, 0
	v_mov_b32_e32 v41, 0
	v_mov_b32_e32 v42, 0
	v_mov_b32_e32 v43, 0
	v_mov_b32_e32 v44, 0
	v_mov_b32_e32 v45, 0
	v_mov_b32_e32 v46, 0
	v_mov_b32_e32 v47, 0
	v_mov_b32_e32 v48, 0
	v_mov_b32_e32 v49, 0
	v_mov_b32_e32 v50, 0
	v_mov_b32_e32 v51, 0
	v_mov_b32_e32 v52, 0
	v_mov_b32_e32 v53, 0
	v_mov_b32_e32 v54, 0
	v_mov_b32_e32 v55, 0
	v_mov_b32_e32 v56, 0
	v_mov_b32_e32 v57, 0
	v_mov_b32_e32 v58, 0
	v_mov_b32_e32 v59, 0
	v_mov_b32_e32 v60, 0
	v_mov_b32_e32 v61, 0
	v_mov_b32_e32 v62, 0
	v_mov_b32_e32 v63, 0
	v_mov_b32_e32 v64, 0
	v_mov_b32_e32 v65, 0
	v_mov_b32_e32 v66, 0
	v_mov_b32_e32 v67, 0
	v_mov_b32_e32 v68, 0
	v_mov_b32_e32 v69, 0
	v_mov_b32_e32 v70, 0
	v_mov_b32_e32 v71, 0
	v_mov_b32_e32 v72, 0
	v_mov_b32_e32 v73, 0
	v_mov_b32_e32 v74, 0
	v_mov_b32_e32 v75, 0
	v_mov_b32_e32 v76, 0
	v_mov_b32_e32 v77, 0
	v_mov_b32_e32 v78, 0
	v_mov_b32_e32 v79, 0
	v_mov_b32_e32 v80, 0
	v_mov_b32_e32 v81, 0
	v_mov_b32_e32 v82, 0
	v_mov_b32_e32 v83, 0
	v_mov_b32_e32 v84, 0
	v_mov_b32_e32 v85, 0
	v_mov_b32_e32 v86, 0
	v_mov_b32_e32 v87, 0
	v_mov_b32_e32 v88, 0
	v_mov_b32_e32 v89, 0
	v_mov_b32_e32 v90, 0
	v_mov_b32_e32 v91, 0
	v_mov_b32_e32 v92, 0
	v_mov_b32_e32 v93, 0
	v_mov_b32_e32 v94, 0
	v_mov_b32_e32 v95, 0
	v_mov_b32_e32 v96, 0
	v_mov_b32_e32 v97, 0
	v_mov_b32_e32 v98, 0
	v_mov_b32_e32 v99, 0
	v_mov_b32_e32 v100, 0
	v_mov_b32_e32 v101, 0
	v_mov_b32_e32 v102, 0
	v_mov_b32_e32 v103, 0
	v_mov_b32_e32 v104, 0
	v_mov_b32_e32 v105, 0
	v_mov_b32_e32 v106, 0
	v_mov_b32_e32 v107, 0
	v_mov_b32_e32 v108, 0
	v_mov_b32_e32 v109, 0
	v_mov_b32_e32 v110, 0
	v_mov_b32_e32 v111, 0
	v_mov_b32_e32 v112, 0
	v_mov_b32_e32 v113, 0
	v_mov_b32_e32 v114, 0
	v_mov_b32_e32 v115, 0
	v_mov_b32_e32 v116, 0
	v_mov_b32_e32 v117, 0
	v_mov_b32_e32 v118, 0
	v_mov_b32_e32 v119, 0
	v_mov_b32_e32 v120, 0
	v_mov_b32_e32 v121, 0
	v_mov_b32_e32 v122, 0
	v_mov_b32_e32 v123, 0
	v_mov_b32_e32 v124, 0
	v_mov_b32_e32 v125, 0
	v_mov_b32_e32 v126, 0
	v_mov_b32_e32 v127, 0
	v_mov_b32_e32 v192, 0
	v_mov_b32_e32 v193, 0
	v_mov_b32_e32 v194, 0
	v_mov_b32_e32 v195, 0
	v_mov_b32_e32 v196, 0
	v_mov_b32_e32 v197, 0
	v_mov_b32_e32 v198, 0
	v_mov_b32_e32 v199, 0
	v_mov_b32_e32 v200, 0
	v_mov_b32_e32 v201, 0
	v_mov_b32_e32 v202, 0
	v_mov_b32_e32 v203, 0
	v_mov_b32_e32 v204, 0
	v_mov_b32_e32 v205, 0
	v_mov_b32_e32 v206, 0
	v_mov_b32_e32 v207, 0
	v_mov_b32_e32 v208, 0
	v_mov_b32_e32 v209, 0
	v_mov_b32_e32 v210, 0
	v_mov_b32_e32 v211, 0
	v_mov_b32_e32 v212, 0
	v_mov_b32_e32 v213, 0
	v_mov_b32_e32 v214, 0
	v_mov_b32_e32 v215, 0
	v_mov_b32_e32 v188, 0
	v_mov_b32_e32 v189, 0
	buffer_load_dwordx4 v[216:219], v160, s[48:51], 0 offen
	buffer_load_dwordx4 v[220:223], v160, s[48:51], s46 offen
	buffer_load_dwordx4 v[224:227], v160, s[48:51], s47 offen
	buffer_load_dwordx4 v[228:231], v160, s[48:51], s58 offen
	buffer_load_dwordx4 v[232:235], v160, s[52:55], 0 offen
	buffer_load_dwordx4 v[236:239], v160, s[52:55], s46 offen
	buffer_load_dwordx4 v[152:155], v160, s[52:55], s47 offen
	buffer_load_dwordx4 v[156:159], v160, s[52:55], s58 offen
	v_add_u32_e32 v160, 0x80, v160
	buffer_load_dwordx4 v[162:165], v160, s[48:51], 0 offen
	buffer_load_dwordx4 v[166:169], v160, s[48:51], s46 offen
	buffer_load_dwordx4 v[176:179], v160, s[48:51], s47 offen
	buffer_load_dwordx4 v[180:183], v160, s[48:51], s58 offen
	buffer_load_dwordx4 v[184:187], v160, s[52:55], 0 offen
	buffer_load_dwordx4 v[242:245], v160, s[52:55], s46 offen
	buffer_load_dwordx4 v[246:249], v160, s[52:55], s47 offen
	buffer_load_dwordx4 v[250:253], v160, s[52:55], s58 offen
	v_add_u32_e32 v160, 0x80, v160
	s_waitcnt vmcnt(8)
	ds_write_b128 v170, v[216:219] offset:0
	ds_write_b128 v170, v[220:223] offset:9216
	ds_write_b128 v170, v[224:227] offset:18432
	ds_write_b128 v170, v[228:231] offset:27648
	ds_write_b128 v171, v[232:235] offset:0
	ds_write_b128 v171, v[236:239] offset:9216
	ds_write_b128 v171, v[152:155] offset:18432
	ds_write_b128 v171, v[156:159] offset:27648
	buffer_load_dwordx4 v[216:219], v160, s[48:51], 0 offen
	buffer_load_dwordx4 v[220:223], v160, s[48:51], s46 offen
	buffer_load_dwordx4 v[224:227], v160, s[48:51], s47 offen
	buffer_load_dwordx4 v[228:231], v160, s[48:51], s58 offen
	buffer_load_dwordx4 v[232:235], v160, s[52:55], 0 offen
	buffer_load_dwordx4 v[236:239], v160, s[52:55], s46 offen
	buffer_load_dwordx4 v[152:155], v160, s[52:55], s47 offen
	buffer_load_dwordx4 v[156:159], v160, s[52:55], s58 offen
	v_add_u32_e32 v160, 0x80, v160
	s_waitcnt lgkmcnt(0)
	s_barrier
	s_movk_i32 s59, 14
